# loop-edge edit in the diff-attention KV loop: rare renorm body moved out of line (common path falls through) and the 8 v_mov_b64 copies of the -mref C operand removed; on top of v48
# baseline (speedup 1.0000x reference)
; #define LAS __attribute__((address_space(3)))
; DI void attn_step32(f32x16& sc, f32x16& sn, f32x16 (&O)[4], const f32x16& negm, float& lsum, float& mrun, const bf16x8 (&qf)[4],
;                     bf16x8 (&kf)[4], const LAS unsigned char* kb_next, bool has_next, const LAS unsigned char* vb, const int (&ko)[4], int vo0, int vo1) {
;     bf16x8 vf[8];
; #pragma unroll
;     for (int cb = 0; cb < 4; ++cb) { vf[cb] = *(const LAS bf16x8*)(vb + vo0 + cb * 4096); vf[4 + cb] = *(const LAS bf16x8*)(vb + vo1 + cb * 4096); }
;     __builtin_amdgcn_sched_barrier(0);
;     sn = negm;
; #pragma unroll
;     for (int ds = 0; ds < 4; ++ds) sn = MFMA32(kf[ds], qf[ds], sn);
;     if (has_next) {
; #pragma unroll
;         for (int ds = 0; ds < 4; ++ds) kf[ds] = *(const LAS bf16x8*)(kb_next + ko[ds]);
;     }
;     __builtin_amdgcn_sched_barrier(0);
;     float mx = max3f(sc[0], sc[1], sc[2]), my = max3f(sc[3], sc[4], sc[5]);
;     mx = max3f(mx, sc[6], sc[7]); my = max3f(my, sc[8], sc[9]); mx = max3f(mx, sc[10], sc[11]); my = max3f(my, sc[12], sc[13]); mx = max3f(mx, sc[14], sc[15]);
;     mrun = max3f(mrun, mx, my);
;     float ps = 0.f;
; #pragma unroll
;     for (int i = 0; i < 16; ++i) { sc[i] = ex2(sc[i]); ps += sc[i]; }
;     lsum += ps;
;     u32x4 w0, w1;
;     w0.x = pk2(sc[0], sc[1]); w0.y = pk2(sc[2], sc[3]); w0.z = pk2(sc[4], sc[5]); w0.w = pk2(sc[6], sc[7]);
;     w1.x = pk2(sc[8], sc[9]); w1.y = pk2(sc[10], sc[11]); w1.z = pk2(sc[12], sc[13]); w1.w = pk2(sc[14], sc[15]);
;     const bf16x8 pf0 = __builtin_bit_cast(bf16x8, w0), pf1 = __builtin_bit_cast(bf16x8, w1);
; #pragma unroll
;     for (int cb = 0; cb < 4; ++cb) O[cb] = MFMA32(vf[cb], pf0, O[cb]);
; #pragma unroll
;     for (int cb = 0; cb < 4; ++cb) O[cb] = MFMA32(vf[4 + cb], pf1, O[cb]);
; }
; DI void diff_attn_phase(int wv, LAS unsigned char* lds, const bf16_t* QK, const bf16_t* VT, int rows, int nb, int S, bf16_t* OUT, const float* lq1, const float* lk1, const float* lq2, const float* lk2, float lam0, float lam1, int layer, const float* gsub) {
;     ...
;             for (int ds = 0; ds < 4; ++ds) kf[ds] = *(const LAS bf16x8*)(KS(0) + 8192 + ko[ds]);
;             attn_step32(sa, sb, O, negm, lsum, mrun, qf, kf, KS(1), true, VS(0), ko, vo[0], vo[1]);
;             attn_step32(sb, sa, O, negm, lsum, mrun, qf, kf, KS(1) + 8192, true, VS(0), ko, vo[2], vo[3]);
.Ldma_skip_a:
	s_setprio 3
	s_add_i32 s33, 0, 0x10000
	v_add_u32_e32 v96, s33, v250
	ds_read_b128 v[112:115], v251 offset:8192
	ds_read_b128 v[116:119], v252 offset:8192
	ds_read_b128 v[120:123], v198 offset:8192
	ds_read_b128 v[124:127], v199 offset:8192
	v_add_u32_e32 v97, s33, v249
	ds_read_b128 v[144:147], v96
	ds_read_b128 v[148:151], v96 offset:4096
	ds_read_b128 v[152:155], v97
	ds_read_b128 v[156:159], v97 offset:4096
	ds_read_b128 v[160:163], v96 offset:8192
	ds_read_b128 v[164:167], v96 offset:12288
	ds_read_b128 v[168:171], v97 offset:8192
	ds_read_b128 v[194:197], v97 offset:12288
	s_waitcnt lgkmcnt(11)
	v_mfma_f32_32x32x16_bf16 v[96:111], v[112:115], v[128:131], v[64:79]
	ds_read_b128 v[220:223], v251 offset:16384
	ds_read_b128 v[224:227], v252 offset:16384
	ds_read_b128 v[228:231], v198 offset:16384
	ds_read_b128 v[232:235], v199 offset:16384
	s_waitcnt lgkmcnt(14)
	v_mfma_f32_32x32x16_bf16 v[96:111], v[116:119], v[132:135], v[96:111]
	s_waitcnt lgkmcnt(13)
	v_mfma_f32_32x32x16_bf16 v[96:111], v[120:123], v[136:139], v[96:111]
	s_waitcnt lgkmcnt(12)
	v_mfma_f32_32x32x16_bf16 v[96:111], v[124:127], v[140:143], v[96:111]
	v_exp_f32_e32 v116, v80
	v_exp_f32_e32 v180, v81
	v_exp_f32_e32 v184, v82
	v_exp_f32_e32 v182, v83
	v_exp_f32_e32 v188, v84
	v_exp_f32_e32 v186, v85
	v_exp_f32_e32 v202, v86
	v_exp_f32_e32 v190, v87
	v_cvt_pk_bf16_f32 v112, v116, v180
	v_cvt_pk_bf16_f32 v113, v184, v182
	v_cvt_pk_bf16_f32 v114, v188, v186
	v_cvt_pk_bf16_f32 v115, v202, v190
	v_exp_f32_e32 v206, v88
	v_exp_f32_e32 v204, v89
	s_waitcnt lgkmcnt(7)
	v_mfma_f32_32x32x16_bf16 v[16:31], v[160:163], v[112:115], v[16:31]
	v_exp_f32_e32 v210, v90
	v_exp_f32_e32 v208, v91
	v_exp_f32_e32 v212, v92
	v_exp_f32_e32 v214, v93
	v_exp_f32_e32 v218, v94
	v_exp_f32_e32 v216, v95
	v_max3_f32 v80, v80, v81, v82
	v_mfma_f32_32x32x16_bf16 v[48:63], v[144:147], v[112:115], v[48:63]
	v_max3_f32 v80, v80, v86, v87
	v_max3_f32 v81, v83, v84, v85
	v_cvt_pk_bf16_f32 v144, v206, v204
	v_max3_f32 v80, v80, v90, v91
	v_max3_f32 v81, v81, v88, v89
	v_cvt_pk_bf16_f32 v145, v210, v208
	v_max3_f32 v80, v80, v94, v95
	v_mfma_f32_32x32x16_bf16 v[32:47], v[148:151], v[112:115], v[32:47]
	v_cvt_pk_bf16_f32 v146, v212, v214
	v_cvt_pk_bf16_f32 v147, v218, v216
	v_max3_f32 v81, v81, v92, v93
	v_mov_b32_e32 v82, 0xf149f2ca
	v_max3_f32 v177, v82, v80, v81
	v_add_u32_e32 v80, s33, v248
	v_add_f32_e32 v192, 0, v116
	s_waitcnt lgkmcnt(6)
	v_mfma_f32_32x32x16_bf16 v[0:15], v[164:167], v[112:115], v[0:15]
	v_add_u32_e32 v81, s33, v247
	s_waitcnt lgkmcnt(5)
	v_mfma_f32_32x32x16_bf16 v[16:31], v[168:171], v[144:147], v[16:31]
	ds_read_b128 v[172:175], v80
	ds_read_b128 v[168:171], v80 offset:4096
	ds_read_b128 v[124:127], v81
	ds_read_b128 v[120:123], v81 offset:4096
	ds_read_b128 v[164:167], v80 offset:8192
	ds_read_b128 v[160:163], v80 offset:12288
	ds_read_b128 v[112:115], v81 offset:8192
	ds_read_b128 v[116:119], v81 offset:12288
	v_mfma_f32_32x32x16_bf16 v[48:63], v[152:155], v[144:147], v[48:63]
	v_mfma_f32_32x32x16_bf16 v[32:47], v[156:159], v[144:147], v[32:47]
	s_waitcnt lgkmcnt(12)
	v_mfma_f32_32x32x16_bf16 v[0:15], v[194:197], v[144:147], v[0:15]
	s_setprio 2
	s_waitcnt lgkmcnt(11)
	v_mfma_f32_32x32x16_bf16 v[80:95], v[220:223], v[128:131], v[64:79]
	ds_read_b128 v[156:159], v251 offset:24576
	ds_read_b128 v[152:155], v252 offset:24576
	ds_read_b128 v[144:147], v198 offset:24576
	ds_read_b128 v[148:151], v199 offset:24576
	s_waitcnt lgkmcnt(14)
	v_mfma_f32_32x32x16_bf16 v[80:95], v[224:227], v[132:135], v[80:95]
	s_waitcnt lgkmcnt(13)
	v_mfma_f32_32x32x16_bf16 v[80:95], v[228:231], v[136:139], v[80:95]
	s_waitcnt lgkmcnt(12)
	v_mfma_f32_32x32x16_bf16 v[80:95], v[232:235], v[140:143], v[80:95]
	v_exp_f32_e32 v181, v96
	v_exp_f32_e32 v185, v97
	v_exp_f32_e32 v183, v98
	v_exp_f32_e32 v189, v99
	v_max3_f32 v178, v96, v97, v98
	v_pk_add_f32 v[96:97], v[180:181], v[192:193]
	v_exp_f32_e32 v187, v100
	v_pk_add_f32 v[96:97], v[184:185], v[96:97]
	v_exp_f32_e32 v203, v101
	v_pk_add_f32 v[96:97], v[182:183], v[96:97]
	v_exp_f32_e32 v191, v102
	v_pk_add_f32 v[96:97], v[188:189], v[96:97]
	v_exp_f32_e32 v207, v103
	v_exp_f32_e32 v205, v104
	v_pk_add_f32 v[96:97], v[186:187], v[96:97]
	v_exp_f32_e32 v211, v105
	v_pk_add_f32 v[96:97], v[202:203], v[96:97]
	v_exp_f32_e32 v209, v106
	v_pk_add_f32 v[96:97], v[190:191], v[96:97]
	v_exp_f32_e32 v213, v107
	v_pk_add_f32 v[96:97], v[206:207], v[96:97]
	v_exp_f32_e32 v215, v108
	v_pk_add_f32 v[96:97], v[204:205], v[96:97]
	v_max3_f32 v179, v99, v100, v101
	v_max3_f32 v178, v178, v102, v103
	v_exp_f32_e32 v219, v109
	v_pk_add_f32 v[96:97], v[210:211], v[96:97]
	v_max3_f32 v179, v179, v104, v105
	v_max3_f32 v178, v178, v106, v107
	v_exp_f32_e32 v217, v110
	v_pk_add_f32 v[96:97], v[208:209], v[96:97]
	v_max3_f32 v179, v179, v108, v109
	v_max3_f32 v178, v178, v110, v111
	v_cvt_pk_bf16_f32 v98, v187, v203
	v_max3_f32 v194, v177, v178, v179
	v_exp_f32_e32 v177, v111
	v_pk_add_f32 v[96:97], v[212:213], v[96:97]
	v_cvt_pk_bf16_f32 v99, v191, v207
	v_pk_add_f32 v[96:97], v[214:215], v[96:97]
	v_cvt_pk_bf16_f32 v100, v205, v211
	v_pk_add_f32 v[96:97], v[218:219], v[96:97]
	v_cvt_pk_bf16_f32 v101, v209, v213
	v_pk_add_f32 v[96:97], v[216:217], v[96:97]
	v_cvt_pk_bf16_f32 v102, v215, v219
	v_pk_add_f32 v[178:179], v[176:177], v[96:97]
	v_cvt_pk_bf16_f32 v96, v181, v185
	v_cvt_pk_bf16_f32 v97, v183, v189
	v_cvt_pk_bf16_f32 v103, v217, v177
	s_add_i32 s33, 0, 0x14000
	s_waitcnt lgkmcnt(7)
	v_mfma_f32_32x32x16_bf16 v[16:31], v[164:167], v[96:99], v[16:31]
	v_mfma_f32_32x32x16_bf16 v[48:63], v[172:175], v[96:99], v[48:63]
	v_mfma_f32_32x32x16_bf16 v[32:47], v[168:171], v[96:99], v[32:47]
	s_waitcnt lgkmcnt(6)
; #define LAS __attribute__((address_space(3)))
; DI float ex2(float x) { return __builtin_amdgcn_exp2f(x); }
; DI void attn_step32(f32x16& sc, f32x16& sn, f32x16 (&O)[4], const f32x16& negm, float& lsum, float& mrun, const bf16x8 (&qf)[4],
;                     bf16x8 (&kf)[4], const LAS unsigned char* kb_next, bool has_next, const LAS unsigned char* vb, const int (&ko)[4], int vo0, int vo1) {
;     bf16x8 vf[8];
; #pragma unroll
;     for (int cb = 0; cb < 4; ++cb) { vf[cb] = *(const LAS bf16x8*)(vb + vo0 + cb * 4096); vf[4 + cb] = *(const LAS bf16x8*)(vb + vo1 + cb * 4096); }
;     __builtin_amdgcn_sched_barrier(0);
;     sn = negm;
; #pragma unroll
;     for (int ds = 0; ds < 4; ++ds) sn = MFMA32(kf[ds], qf[ds], sn);
;     if (has_next) {
; #pragma unroll
;         for (int ds = 0; ds < 4; ++ds) kf[ds] = *(const LAS bf16x8*)(kb_next + ko[ds]);
;     }
;     __builtin_amdgcn_sched_barrier(0);
;     float mx = max3f(sc[0], sc[1], sc[2]), my = max3f(sc[3], sc[4], sc[5]);
;     mx = max3f(mx, sc[6], sc[7]); my = max3f(my, sc[8], sc[9]); mx = max3f(mx, sc[10], sc[11]); my = max3f(my, sc[12], sc[13]); mx = max3f(mx, sc[14], sc[15]);
;     mrun = max3f(mrun, mx, my);
;     float ps = 0.f;
; #pragma unroll
;     for (int i = 0; i < 16; ++i) { sc[i] = ex2(sc[i]); ps += sc[i]; }
;     lsum += ps;
;     u32x4 w0, w1;
;     w0.x = pk2(sc[0], sc[1]); w0.y = pk2(sc[2], sc[3]); w0.z = pk2(sc[4], sc[5]); w0.w = pk2(sc[6], sc[7]);
;     w1.x = pk2(sc[8], sc[9]); w1.y = pk2(sc[10], sc[11]); w1.z = pk2(sc[12], sc[13]); w1.w = pk2(sc[14], sc[15]);
;     const bf16x8 pf0 = __builtin_bit_cast(bf16x8, w0), pf1 = __builtin_bit_cast(bf16x8, w1);
; #pragma unroll
;     for (int cb = 0; cb < 4; ++cb) O[cb] = MFMA32(vf[cb], pf0, O[cb]);
; #pragma unroll
;     for (int cb = 0; cb < 4; ++cb) O[cb] = MFMA32(vf[4 + cb], pf1, O[cb]);
; }
; DI void attn_renorm(f32x16& spend, f32x16 (&O)[4], f32x16& negm, float& mref, float& lsum, float& mrun) {
;     constexpr float THR = 6.0f;
;     const float mx = swap_max(mrun);
;     if (__any(mx > THR)) {
;         const float dl = fmaxf(mx, 0.f), alpha = ex2(-dl);
;         mref += dl; lsum *= alpha;
; #pragma unroll
;         for (int cb = 0; cb < 4; ++cb) O[cb] = O[cb] * alpha;
; #pragma unroll
;         for (int i = 0; i < 16; ++i) { spend[i] -= dl; negm[i] = -mref; }
;     }
;     mrun = -1.0e30f;
; }
	v_mfma_f32_32x32x16_bf16 v[0:15], v[160:163], v[96:99], v[0:15]
	s_waitcnt lgkmcnt(5)
	v_mfma_f32_32x32x16_bf16 v[16:31], v[112:115], v[100:103], v[16:31]
	v_add_u32_e32 v112, s33, v250
	v_add_u32_e32 v113, s33, v249
	ds_read_b128 v[96:99], v112
	v_mfma_f32_32x32x16_bf16 v[48:63], v[124:127], v[100:103], v[48:63]
	v_mfma_f32_32x32x16_bf16 v[32:47], v[120:123], v[100:103], v[32:47]
	s_waitcnt lgkmcnt(5)
	v_mfma_f32_32x32x16_bf16 v[0:15], v[116:119], v[100:103], v[0:15]
	ds_read_b128 v[100:103], v113
	ds_read_b128 v[104:107], v112 offset:4096
	ds_read_b128 v[108:111], v113 offset:4096
	ds_read_b128 v[174:177], v112 offset:8192
	ds_read_b128 v[202:205], v113 offset:8192
	ds_read_b128 v[186:189], v112 offset:12288
	ds_read_b128 v[206:209], v113 offset:12288
	s_setprio 1
	s_waitcnt lgkmcnt(11)
	v_mfma_f32_32x32x16_bf16 v[112:127], v[156:159], v[128:131], v[64:79]
	ds_read_b128 v[210:213], v251 offset:32768
	ds_read_b128 v[214:217], v252 offset:32768
	ds_read_b128 v[218:221], v198 offset:32768
	ds_read_b128 v[222:225], v199 offset:32768
	s_waitcnt lgkmcnt(14)
	v_mfma_f32_32x32x16_bf16 v[112:127], v[152:155], v[132:135], v[112:127]
	s_waitcnt lgkmcnt(13)
	v_mfma_f32_32x32x16_bf16 v[112:127], v[144:147], v[136:139], v[112:127]
	s_waitcnt lgkmcnt(12)
	v_mfma_f32_32x32x16_bf16 v[112:127], v[148:151], v[140:143], v[112:127]
	v_exp_f32_e32 v148, v80
	v_exp_f32_e32 v160, v81
	v_exp_f32_e32 v164, v82
	v_exp_f32_e32 v162, v83
	v_exp_f32_e32 v168, v84
	v_exp_f32_e32 v166, v85
	v_exp_f32_e32 v172, v86
	v_exp_f32_e32 v170, v87
	v_cvt_pk_bf16_f32 v144, v148, v160
	v_cvt_pk_bf16_f32 v145, v164, v162
	v_cvt_pk_bf16_f32 v146, v168, v166
	v_cvt_pk_bf16_f32 v147, v172, v170
	v_max3_f32 v80, v80, v81, v82
	v_max3_f32 v81, v83, v84, v85
	v_exp_f32_e32 v182, v90
	v_max3_f32 v80, v80, v86, v87
	v_exp_f32_e32 v180, v91
	s_waitcnt lgkmcnt(11)
	v_mfma_f32_32x32x16_bf16 v[48:63], v[96:99], v[144:147], v[48:63]
	v_max3_f32 v80, v80, v90, v91
	v_exp_f32_e32 v184, v92
	v_exp_f32_e32 v190, v94
	v_max3_f32 v81, v81, v88, v89
	v_max3_f32 v80, v80, v94, v95
	v_add_u32_e32 v84, s33, v247
	v_max3_f32 v81, v81, v92, v93
	s_waitcnt lgkmcnt(9)
	v_mfma_f32_32x32x16_bf16 v[32:47], v[104:107], v[144:147], v[32:47]
	v_max3_f32 v161, v194, v80, v81
	v_add_u32_e32 v80, s33, v248
	v_add_f32_e32 v192, 0, v148
	v_cvt_pk_bf16_f32 v97, v182, v180
	s_waitcnt lgkmcnt(7)
	v_mfma_f32_32x32x16_bf16 v[16:31], v[174:177], v[144:147], v[16:31]
	v_exp_f32_e32 v176, v88
	v_exp_f32_e32 v174, v89
	s_nop 0
	v_cvt_pk_bf16_f32 v96, v176, v174
	s_waitcnt lgkmcnt(5)
	v_mfma_f32_32x32x16_bf16 v[0:15], v[186:189], v[144:147], v[0:15]
	v_exp_f32_e32 v186, v93
	v_exp_f32_e32 v188, v95
	ds_read_b128 v[156:159], v80
	ds_read_b128 v[152:155], v80 offset:4096
	ds_read_b128 v[92:95], v84
	ds_read_b128 v[88:91], v84 offset:4096
	ds_read_b128 v[148:151], v80 offset:8192
	ds_read_b128 v[144:147], v80 offset:12288
	ds_read_b128 v[80:83], v84 offset:8192
	ds_read_b128 v[84:87], v84 offset:12288
	v_cvt_pk_bf16_f32 v98, v184, v186
	v_cvt_pk_bf16_f32 v99, v190, v188
	s_nop 1
	v_mfma_f32_32x32x16_bf16 v[48:63], v[100:103], v[96:99], v[48:63]
	v_mfma_f32_32x32x16_bf16 v[32:47], v[108:111], v[96:99], v[32:47]
	v_mfma_f32_32x32x16_bf16 v[16:31], v[202:205], v[96:99], v[16:31]
	s_waitcnt lgkmcnt(12)
	v_mfma_f32_32x32x16_bf16 v[0:15], v[206:209], v[96:99], v[0:15]
	s_setprio 0
	s_waitcnt lgkmcnt(11)
	v_mfma_f32_32x32x16_bf16 v[96:111], v[210:213], v[128:131], v[64:79]
	s_waitcnt lgkmcnt(10)
	v_mfma_f32_32x32x16_bf16 v[96:111], v[214:217], v[132:135], v[96:111]
	s_waitcnt lgkmcnt(9)
	v_mfma_f32_32x32x16_bf16 v[96:111], v[218:221], v[136:139], v[96:111]
	s_waitcnt lgkmcnt(8)
	v_mfma_f32_32x32x16_bf16 v[96:111], v[222:225], v[140:143], v[96:111]
	v_max3_f32 v163, v112, v113, v114
	v_max3_f32 v165, v115, v116, v117
	v_exp_f32_e32 v169, v115
	v_max3_f32 v163, v163, v118, v119
	v_max3_f32 v165, v165, v120, v121
	v_exp_f32_e32 v167, v116
	v_max3_f32 v163, v163, v122, v123
	v_max3_f32 v165, v165, v124, v125
	v_exp_f32_e32 v173, v117
	v_max3_f32 v163, v163, v126, v127
	v_exp_f32_e32 v171, v118
	v_max3_f32 v194, v161, v163, v165
	v_exp_f32_e32 v161, v112
	v_exp_f32_e32 v165, v113
	v_exp_f32_e32 v163, v114
	v_exp_f32_e32 v177, v119
	v_pk_add_f32 v[112:113], v[160:161], v[192:193]
	v_exp_f32_e32 v175, v120
	v_pk_add_f32 v[112:113], v[164:165], v[112:113]
	v_exp_f32_e32 v183, v121
	v_pk_add_f32 v[112:113], v[162:163], v[112:113]
	v_exp_f32_e32 v181, v122
	v_pk_add_f32 v[112:113], v[168:169], v[112:113]
	v_exp_f32_e32 v185, v123
	v_pk_add_f32 v[112:113], v[166:167], v[112:113]
	v_exp_f32_e32 v187, v124
	v_pk_add_f32 v[112:113], v[172:173], v[112:113]
	v_exp_f32_e32 v191, v125
	v_pk_add_f32 v[112:113], v[170:171], v[112:113]
	v_exp_f32_e32 v189, v126
	v_pk_add_f32 v[112:113], v[176:177], v[112:113]
	v_exp_f32_e32 v119, v127
	v_pk_add_f32 v[112:113], v[174:175], v[112:113]
	v_pk_add_f32 v[114:115], v[178:179], v[178:179] op_sel:[0,1] op_sel_hi:[1,0]
	v_pk_add_f32 v[112:113], v[182:183], v[112:113]
	v_mov_b32_e32 v115, v119
	v_pk_add_f32 v[112:113], v[180:181], v[112:113]
	v_cvt_pk_bf16_f32 v116, v175, v183
	v_pk_add_f32 v[112:113], v[184:185], v[112:113]
	v_cvt_pk_bf16_f32 v117, v181, v185
	v_pk_add_f32 v[112:113], v[186:187], v[112:113]
	v_cvt_pk_bf16_f32 v118, v187, v191
	v_pk_add_f32 v[112:113], v[190:191], v[112:113]
	v_cvt_pk_bf16_f32 v119, v189, v119
	v_pk_add_f32 v[112:113], v[188:189], v[112:113]
	s_nop 0
	v_pk_add_f32 v[112:113], v[114:115], v[112:113]
	v_cvt_pk_bf16_f32 v114, v167, v173
	v_add_f32_e32 v202, v112, v113
	v_cvt_pk_bf16_f32 v112, v161, v165
	v_cvt_pk_bf16_f32 v113, v163, v169
	v_cvt_pk_bf16_f32 v115, v171, v177
	s_waitcnt lgkmcnt(7)
	s_nop 0
	v_mfma_f32_32x32x16_bf16 v[48:63], v[156:159], v[112:115], v[48:63]
	s_waitcnt lgkmcnt(6)
	v_mfma_f32_32x32x16_bf16 v[32:47], v[152:155], v[112:115], v[32:47]
	s_waitcnt lgkmcnt(3)
	v_mfma_f32_32x32x16_bf16 v[16:31], v[148:151], v[112:115], v[16:31]
	s_waitcnt lgkmcnt(2)
	v_mfma_f32_32x32x16_bf16 v[0:15], v[144:147], v[112:115], v[0:15]
	v_mfma_f32_32x32x16_bf16 v[48:63], v[92:95], v[116:119], v[48:63]
	v_mfma_f32_32x32x16_bf16 v[32:47], v[88:91], v[116:119], v[32:47]
	s_waitcnt lgkmcnt(1)
	v_mfma_f32_32x32x16_bf16 v[16:31], v[80:83], v[116:119], v[16:31]
	v_mov_b32_e32 v80, v194
	s_nop 1
	v_permlane32_swap_b32_e32 v194, v80
	v_max_f32_e32 v80, v80, v80
	v_max_f32_e32 v81, v194, v194
	v_max_f32_e32 v80, v81, v80
	v_cmp_lt_f32_e32 vcc, s95, v80
	s_waitcnt lgkmcnt(0)
	v_mfma_f32_32x32x16_bf16 v[0:15], v[84:87], v[116:119], v[0:15]
	s_cbranch_vccnz .Lrenorm_a

; #define LAS __attribute__((address_space(3)))
; DI void attn_step32(f32x16& sc, f32x16& sn, f32x16 (&O)[4], const f32x16& negm, float& lsum, float& mrun, const bf16x8 (&qf)[4],
;                     bf16x8 (&kf)[4], const LAS unsigned char* kb_next, bool has_next, const LAS unsigned char* vb, const int (&ko)[4], int vo0, int vo1) {
;     bf16x8 vf[8];
; #pragma unroll
;     for (int cb = 0; cb < 4; ++cb) { vf[cb] = *(const LAS bf16x8*)(vb + vo0 + cb * 4096); vf[4 + cb] = *(const LAS bf16x8*)(vb + vo1 + cb * 4096); }
;     __builtin_amdgcn_sched_barrier(0);
;     sn = negm;
; #pragma unroll
;     for (int ds = 0; ds < 4; ++ds) sn = MFMA32(kf[ds], qf[ds], sn);
;     if (has_next) {
; #pragma unroll
;         for (int ds = 0; ds < 4; ++ds) kf[ds] = *(const LAS bf16x8*)(kb_next + ko[ds]);
;     }
;     __builtin_amdgcn_sched_barrier(0);
;     float mx = max3f(sc[0], sc[1], sc[2]), my = max3f(sc[3], sc[4], sc[5]);
;     mx = max3f(mx, sc[6], sc[7]); my = max3f(my, sc[8], sc[9]); mx = max3f(mx, sc[10], sc[11]); my = max3f(my, sc[12], sc[13]); mx = max3f(mx, sc[14], sc[15]);
;     mrun = max3f(mrun, mx, my);
;     float ps = 0.f;
; #pragma unroll
;     for (int i = 0; i < 16; ++i) { sc[i] = ex2(sc[i]); ps += sc[i]; }
;     lsum += ps;
;     u32x4 w0, w1;
;     w0.x = pk2(sc[0], sc[1]); w0.y = pk2(sc[2], sc[3]); w0.z = pk2(sc[4], sc[5]); w0.w = pk2(sc[6], sc[7]);
;     w1.x = pk2(sc[8], sc[9]); w1.y = pk2(sc[10], sc[11]); w1.z = pk2(sc[12], sc[13]); w1.w = pk2(sc[14], sc[15]);
;     const bf16x8 pf0 = __builtin_bit_cast(bf16x8, w0), pf1 = __builtin_bit_cast(bf16x8, w1);
; #pragma unroll
;     for (int cb = 0; cb < 4; ++cb) O[cb] = MFMA32(vf[cb], pf0, O[cb]);
; #pragma unroll
;     for (int cb = 0; cb < 4; ++cb) O[cb] = MFMA32(vf[4 + cb], pf1, O[cb]);
; }
; DI void diff_attn_phase(int wv, LAS unsigned char* lds, const bf16_t* QK, const bf16_t* VT, int rows, int nb, int S, bf16_t* OUT, const float* lq1, const float* lk1, const float* lq2, const float* lk2, float lam0, float lam1, int layer, const float* gsub) {
;     ...
;             for (int ds = 0; ds < 4; ++ds) kf[ds] = *(const LAS bf16x8*)(KS(2) + 8192 + ko[ds]);
;             attn_step32(sa, sb, O, negm, lsum, mrun, qf, kf, KS(3), true, VS(2), ko, vo[0], vo[1]);
;             attn_step32(sb, sa, O, negm, lsum, mrun, qf, kf, KS(3) + 8192, true, VS(2), ko, vo[2], vo[3]);
.Ldma_skip_b:
	s_setprio 3
	s_add_i32 s20, 0, 0x18000
	v_add_u32_e32 v112, s20, v250
	ds_read_b128 v[144:147], v251 offset:40960
	ds_read_b128 v[148:151], v252 offset:40960
	ds_read_b128 v[152:155], v198 offset:40960
	ds_read_b128 v[156:159], v199 offset:40960
	v_add_u32_e32 v113, s20, v249
	ds_read_b128 v[160:163], v112
	ds_read_b128 v[164:167], v112 offset:4096
	ds_read_b128 v[168:171], v113
	ds_read_b128 v[172:175], v113 offset:4096
	ds_read_b128 v[176:179], v112 offset:8192
	ds_read_b128 v[180:183], v112 offset:12288
	ds_read_b128 v[184:187], v113 offset:8192
	ds_read_b128 v[194:197], v113 offset:12288
	s_waitcnt lgkmcnt(11)
	v_mfma_f32_32x32x16_bf16 v[112:127], v[144:147], v[128:131], v[64:79]
	s_waitcnt lgkmcnt(10)
	v_mfma_f32_32x32x16_bf16 v[112:127], v[148:151], v[132:135], v[112:127]
	s_waitcnt lgkmcnt(9)
	v_mfma_f32_32x32x16_bf16 v[112:127], v[152:155], v[136:139], v[112:127]
	s_waitcnt lgkmcnt(8)
	v_mfma_f32_32x32x16_bf16 v[112:127], v[156:159], v[140:143], v[112:127]
	ds_read_b128 v[144:147], v251 offset:49152
	ds_read_b128 v[148:151], v252 offset:49152
	ds_read_b128 v[152:155], v198 offset:49152
	ds_read_b128 v[156:159], v199 offset:49152
	v_exp_f32_e32 v192, v96
	v_exp_f32_e32 v206, v97
	v_exp_f32_e32 v210, v98
	v_exp_f32_e32 v208, v99
	v_exp_f32_e32 v214, v100
	v_exp_f32_e32 v212, v101
	v_exp_f32_e32 v218, v102
	v_exp_f32_e32 v216, v103
	v_cvt_pk_bf16_f32 v188, v192, v206
	v_cvt_pk_bf16_f32 v189, v210, v208
	v_cvt_pk_bf16_f32 v190, v214, v212
	v_cvt_pk_bf16_f32 v191, v218, v216
	v_exp_f32_e32 v222, v104
	v_exp_f32_e32 v220, v105
	s_waitcnt lgkmcnt(11)
	v_mfma_f32_32x32x16_bf16 v[48:63], v[160:163], v[188:191], v[48:63]
	v_exp_f32_e32 v226, v106
	v_exp_f32_e32 v224, v107
	v_exp_f32_e32 v228, v108
	v_exp_f32_e32 v230, v109
	v_exp_f32_e32 v234, v110
	v_exp_f32_e32 v232, v111
	v_max3_f32 v96, v96, v97, v98
	s_waitcnt lgkmcnt(10)
	v_mfma_f32_32x32x16_bf16 v[32:47], v[164:167], v[188:191], v[32:47]
	v_max3_f32 v96, v96, v102, v103
	v_max3_f32 v97, v99, v100, v101
	v_cvt_pk_bf16_f32 v236, v222, v220
	v_max3_f32 v96, v96, v106, v107
	v_max3_f32 v97, v97, v104, v105
	v_cvt_pk_bf16_f32 v237, v226, v224
	v_max3_f32 v96, v96, v110, v111
	s_waitcnt lgkmcnt(7)
	v_mfma_f32_32x32x16_bf16 v[16:31], v[176:179], v[188:191], v[16:31]
	v_cvt_pk_bf16_f32 v238, v228, v230
	v_cvt_pk_bf16_f32 v239, v234, v232
	v_max3_f32 v97, v97, v108, v109
	v_mov_b32_e32 v98, 0xf149f2ca
	v_max3_f32 v201, v98, v96, v97
	v_add_u32_e32 v96, s20, v248
	v_add_u32_e32 v97, s20, v247
	s_waitcnt lgkmcnt(6)
	v_mfma_f32_32x32x16_bf16 v[0:15], v[180:183], v[188:191], v[0:15]
	v_add_f32_e32 v192, 0, v192
	v_mfma_f32_32x32x16_bf16 v[48:63], v[168:171], v[236:239], v[48:63]
	v_mfma_f32_32x32x16_bf16 v[32:47], v[172:175], v[236:239], v[32:47]
	s_waitcnt lgkmcnt(5)
	v_mfma_f32_32x32x16_bf16 v[16:31], v[184:187], v[236:239], v[16:31]
	ds_read_b128 v[188:191], v96
	ds_read_b128 v[184:187], v96 offset:4096
	ds_read_b128 v[172:175], v97
	ds_read_b128 v[168:171], v97 offset:4096
	ds_read_b128 v[180:183], v96 offset:8192
	ds_read_b128 v[176:179], v96 offset:12288
	ds_read_b128 v[160:163], v97 offset:8192
	ds_read_b128 v[164:167], v97 offset:12288
	s_waitcnt lgkmcnt(12)
	v_mfma_f32_32x32x16_bf16 v[0:15], v[194:197], v[236:239], v[0:15]
	s_setprio 2
	s_waitcnt lgkmcnt(11)
	v_mfma_f32_32x32x16_bf16 v[96:111], v[144:147], v[128:131], v[64:79]
	s_waitcnt lgkmcnt(10)
	v_mfma_f32_32x32x16_bf16 v[96:111], v[148:151], v[132:135], v[96:111]
	s_waitcnt lgkmcnt(9)
	v_mfma_f32_32x32x16_bf16 v[96:111], v[152:155], v[136:139], v[96:111]
	s_waitcnt lgkmcnt(8)
	v_mfma_f32_32x32x16_bf16 v[96:111], v[156:159], v[140:143], v[96:111]
	ds_read_b128 v[156:159], v251 offset:57344
	ds_read_b128 v[152:155], v252 offset:57344
	ds_read_b128 v[144:147], v198 offset:57344
	ds_read_b128 v[148:151], v199 offset:57344
	v_exp_f32_e32 v207, v112
	v_exp_f32_e32 v211, v113
	v_exp_f32_e32 v209, v114
	v_exp_f32_e32 v215, v115
	v_max3_f32 v194, v112, v113, v114
	v_pk_add_f32 v[112:113], v[206:207], v[192:193]
	v_exp_f32_e32 v213, v116
	v_pk_add_f32 v[112:113], v[210:211], v[112:113]
	v_exp_f32_e32 v219, v117
	v_pk_add_f32 v[112:113], v[208:209], v[112:113]
	v_exp_f32_e32 v217, v118
	v_pk_add_f32 v[112:113], v[214:215], v[112:113]
	v_exp_f32_e32 v223, v119
	v_exp_f32_e32 v221, v120
	v_pk_add_f32 v[112:113], v[212:213], v[112:113]
	v_exp_f32_e32 v227, v121
	v_pk_add_f32 v[112:113], v[218:219], v[112:113]
	v_exp_f32_e32 v225, v122
	v_pk_add_f32 v[112:113], v[216:217], v[112:113]
	v_exp_f32_e32 v229, v123
	v_pk_add_f32 v[112:113], v[222:223], v[112:113]
	v_exp_f32_e32 v231, v124
	v_pk_add_f32 v[112:113], v[220:221], v[112:113]
	v_exp_f32_e32 v235, v125
	v_pk_add_f32 v[112:113], v[226:227], v[112:113]
	v_exp_f32_e32 v233, v126
	v_pk_add_f32 v[112:113], v[224:225], v[112:113]
	v_exp_f32_e32 v203, v127
	v_pk_add_f32 v[112:113], v[228:229], v[112:113]
	v_max3_f32 v195, v115, v116, v117
	v_cvt_pk_bf16_f32 v114, v213, v219
	v_pk_add_f32 v[112:113], v[230:231], v[112:113]
	v_cvt_pk_bf16_f32 v115, v217, v223
	v_pk_add_f32 v[112:113], v[234:235], v[112:113]
	s_add_i32 s20, 0, 0x1c000
	v_pk_add_f32 v[112:113], v[232:233], v[112:113]
	v_max3_f32 v194, v194, v118, v119
	v_cvt_pk_bf16_f32 v116, v221, v227
	v_pk_add_f32 v[204:205], v[202:203], v[112:113]
	v_cvt_pk_bf16_f32 v112, v207, v211
	v_cvt_pk_bf16_f32 v113, v209, v215
	v_cvt_pk_bf16_f32 v117, v225, v229
	v_cvt_pk_bf16_f32 v118, v231, v235
	s_waitcnt lgkmcnt(11)
	v_mfma_f32_32x32x16_bf16 v[48:63], v[188:191], v[112:115], v[48:63]
	v_cvt_pk_bf16_f32 v119, v233, v203
	v_max3_f32 v194, v194, v122, v123
	v_max3_f32 v195, v195, v120, v121
	s_nop 0
	v_max3_f32 v194, v194, v126, v127
	v_max3_f32 v195, v195, v124, v125
	s_waitcnt lgkmcnt(10)
; #define LAS __attribute__((address_space(3)))
; DI float ex2(float x) { return __builtin_amdgcn_exp2f(x); }
; DI void attn_step32(f32x16& sc, f32x16& sn, f32x16 (&O)[4], const f32x16& negm, float& lsum, float& mrun, const bf16x8 (&qf)[4],
;                     bf16x8 (&kf)[4], const LAS unsigned char* kb_next, bool has_next, const LAS unsigned char* vb, const int (&ko)[4], int vo0, int vo1) {
;     bf16x8 vf[8];
; #pragma unroll
;     for (int cb = 0; cb < 4; ++cb) { vf[cb] = *(const LAS bf16x8*)(vb + vo0 + cb * 4096); vf[4 + cb] = *(const LAS bf16x8*)(vb + vo1 + cb * 4096); }
;     __builtin_amdgcn_sched_barrier(0);
;     sn = negm;
; #pragma unroll
;     for (int ds = 0; ds < 4; ++ds) sn = MFMA32(kf[ds], qf[ds], sn);
;     if (has_next) {
; #pragma unroll
;         for (int ds = 0; ds < 4; ++ds) kf[ds] = *(const LAS bf16x8*)(kb_next + ko[ds]);
;     }
;     __builtin_amdgcn_sched_barrier(0);
;     float mx = max3f(sc[0], sc[1], sc[2]), my = max3f(sc[3], sc[4], sc[5]);
;     mx = max3f(mx, sc[6], sc[7]); my = max3f(my, sc[8], sc[9]); mx = max3f(mx, sc[10], sc[11]); my = max3f(my, sc[12], sc[13]); mx = max3f(mx, sc[14], sc[15]);
;     mrun = max3f(mrun, mx, my);
;     float ps = 0.f;
; #pragma unroll
;     for (int i = 0; i < 16; ++i) { sc[i] = ex2(sc[i]); ps += sc[i]; }
;     lsum += ps;
;     u32x4 w0, w1;
;     w0.x = pk2(sc[0], sc[1]); w0.y = pk2(sc[2], sc[3]); w0.z = pk2(sc[4], sc[5]); w0.w = pk2(sc[6], sc[7]);
;     w1.x = pk2(sc[8], sc[9]); w1.y = pk2(sc[10], sc[11]); w1.z = pk2(sc[12], sc[13]); w1.w = pk2(sc[14], sc[15]);
;     const bf16x8 pf0 = __builtin_bit_cast(bf16x8, w0), pf1 = __builtin_bit_cast(bf16x8, w1);
; #pragma unroll
;     for (int cb = 0; cb < 4; ++cb) O[cb] = MFMA32(vf[cb], pf0, O[cb]);
; #pragma unroll
;     for (int cb = 0; cb < 4; ++cb) O[cb] = MFMA32(vf[4 + cb], pf1, O[cb]);
; }
; DI void attn_renorm(f32x16& spend, f32x16 (&O)[4], f32x16& negm, float& mref, float& lsum, float& mrun) {
;     constexpr float THR = 6.0f;
;     const float mx = swap_max(mrun);
;     if (__any(mx > THR)) {
;         const float dl = fmaxf(mx, 0.f), alpha = ex2(-dl);
;         mref += dl; lsum *= alpha;
; #pragma unroll
;         for (int cb = 0; cb < 4; ++cb) O[cb] = O[cb] * alpha;
; #pragma unroll
;         for (int i = 0; i < 16; ++i) { spend[i] -= dl; negm[i] = -mref; }
;     }
;     mrun = -1.0e30f;
; }
	v_mfma_f32_32x32x16_bf16 v[32:47], v[184:187], v[112:115], v[32:47]
	v_max3_f32 v194, v201, v194, v195
	s_waitcnt lgkmcnt(7)
	v_mfma_f32_32x32x16_bf16 v[16:31], v[180:183], v[112:115], v[16:31]
	s_waitcnt lgkmcnt(6)
	v_mfma_f32_32x32x16_bf16 v[0:15], v[176:179], v[112:115], v[0:15]
	v_add_u32_e32 v112, s20, v250
	v_add_u32_e32 v113, s20, v249
	v_mfma_f32_32x32x16_bf16 v[48:63], v[172:175], v[116:119], v[48:63]
	ds_read_b128 v[174:177], v112
	ds_read_b128 v[206:209], v113
	ds_read_b128 v[178:181], v112 offset:4096
	ds_read_b128 v[210:213], v113 offset:4096
	ds_read_b128 v[182:185], v112 offset:8192
	ds_read_b128 v[214:217], v113 offset:8192
	ds_read_b128 v[186:189], v112 offset:12288
	ds_read_b128 v[218:221], v113 offset:12288
	v_mfma_f32_32x32x16_bf16 v[32:47], v[168:171], v[116:119], v[32:47]
	s_waitcnt lgkmcnt(13)
	v_mfma_f32_32x32x16_bf16 v[16:31], v[160:163], v[116:119], v[16:31]
	s_waitcnt lgkmcnt(12)
	v_mfma_f32_32x32x16_bf16 v[0:15], v[164:167], v[116:119], v[0:15]
	s_setprio 1
	s_waitcnt lgkmcnt(11)
	v_mfma_f32_32x32x16_bf16 v[112:127], v[156:159], v[128:131], v[64:79]
	ds_read_b128 v[222:225], v251
	ds_read_b128 v[226:229], v252
	ds_read_b128 v[230:233], v198
	ds_read_b128 v[234:237], v199
	s_waitcnt lgkmcnt(14)
	v_mfma_f32_32x32x16_bf16 v[112:127], v[152:155], v[132:135], v[112:127]
	s_waitcnt lgkmcnt(13)
	v_mfma_f32_32x32x16_bf16 v[112:127], v[144:147], v[136:139], v[112:127]
	s_waitcnt lgkmcnt(12)
	v_mfma_f32_32x32x16_bf16 v[112:127], v[148:151], v[140:143], v[112:127]
	v_exp_f32_e32 v148, v96
	v_exp_f32_e32 v160, v97
	v_exp_f32_e32 v164, v98
	v_exp_f32_e32 v162, v99
	v_exp_f32_e32 v168, v100
	v_exp_f32_e32 v166, v101
	v_exp_f32_e32 v172, v102
	v_exp_f32_e32 v170, v103
	v_cvt_pk_bf16_f32 v144, v148, v160
	v_cvt_pk_bf16_f32 v145, v164, v162
	v_cvt_pk_bf16_f32 v146, v168, v166
	v_cvt_pk_bf16_f32 v147, v172, v170
	v_max3_f32 v96, v96, v97, v98
	v_max3_f32 v97, v99, v100, v101
	v_add_u32_e32 v100, s20, v247
	v_max3_f32 v96, v96, v102, v103
	v_max3_f32 v97, v97, v104, v105
	s_waitcnt lgkmcnt(11)
	v_mfma_f32_32x32x16_bf16 v[48:63], v[174:177], v[144:147], v[48:63]
	v_max3_f32 v96, v96, v106, v107
	v_exp_f32_e32 v176, v104
	v_exp_f32_e32 v174, v105
	v_max3_f32 v96, v96, v110, v111
	v_max3_f32 v97, v97, v108, v109
	v_add_f32_e32 v192, 0, v148
	v_max3_f32 v161, v194, v96, v97
	s_waitcnt lgkmcnt(9)
	v_mfma_f32_32x32x16_bf16 v[32:47], v[178:181], v[144:147], v[32:47]
	v_exp_f32_e32 v180, v106
	v_exp_f32_e32 v178, v107
	v_add_u32_e32 v96, s20, v248
	v_cvt_pk_bf16_f32 v238, v176, v174
	v_cvt_pk_bf16_f32 v239, v180, v178
	s_waitcnt lgkmcnt(7)
	v_mfma_f32_32x32x16_bf16 v[16:31], v[182:185], v[144:147], v[16:31]
	v_exp_f32_e32 v182, v108
	v_exp_f32_e32 v184, v109
	s_nop 0
	v_cvt_pk_bf16_f32 v240, v182, v184
	s_waitcnt lgkmcnt(5)
	v_mfma_f32_32x32x16_bf16 v[0:15], v[186:189], v[144:147], v[0:15]
	v_exp_f32_e32 v188, v110
	v_exp_f32_e32 v186, v111
	ds_read_b128 v[156:159], v96
	ds_read_b128 v[152:155], v96 offset:4096
	ds_read_b128 v[108:111], v100
	ds_read_b128 v[104:107], v100 offset:4096
	ds_read_b128 v[148:151], v96 offset:8192
	ds_read_b128 v[144:147], v96 offset:12288
	ds_read_b128 v[96:99], v100 offset:8192
	ds_read_b128 v[100:103], v100 offset:12288
	v_cvt_pk_bf16_f32 v241, v188, v186
	s_nop 1
	v_mfma_f32_32x32x16_bf16 v[48:63], v[206:209], v[238:241], v[48:63]
	v_mfma_f32_32x32x16_bf16 v[32:47], v[210:213], v[238:241], v[32:47]
	v_mfma_f32_32x32x16_bf16 v[16:31], v[214:217], v[238:241], v[16:31]
	s_waitcnt lgkmcnt(12)
	v_mfma_f32_32x32x16_bf16 v[0:15], v[218:221], v[238:241], v[0:15]
	s_setprio 0
	s_waitcnt lgkmcnt(11)
	v_mfma_f32_32x32x16_bf16 v[80:95], v[222:225], v[128:131], v[64:79]
	s_waitcnt lgkmcnt(10)
	v_mfma_f32_32x32x16_bf16 v[80:95], v[226:229], v[132:135], v[80:95]
	s_waitcnt lgkmcnt(9)
	v_mfma_f32_32x32x16_bf16 v[80:95], v[230:233], v[136:139], v[80:95]
	s_waitcnt lgkmcnt(8)
	v_mfma_f32_32x32x16_bf16 v[80:95], v[234:237], v[140:143], v[80:95]
	v_max3_f32 v163, v112, v113, v114
	v_max3_f32 v165, v115, v116, v117
	v_exp_f32_e32 v169, v115
	v_max3_f32 v163, v163, v118, v119
	v_max3_f32 v165, v165, v120, v121
	v_exp_f32_e32 v167, v116
	v_max3_f32 v163, v163, v122, v123
	v_max3_f32 v165, v165, v124, v125
	v_exp_f32_e32 v173, v117
	v_max3_f32 v163, v163, v126, v127
	v_exp_f32_e32 v171, v118
	v_max3_f32 v190, v161, v163, v165
	v_exp_f32_e32 v161, v112
	v_exp_f32_e32 v165, v113
	v_exp_f32_e32 v163, v114
	v_exp_f32_e32 v177, v119
	v_pk_add_f32 v[112:113], v[160:161], v[192:193]
	v_exp_f32_e32 v175, v120
	v_pk_add_f32 v[112:113], v[164:165], v[112:113]
	v_exp_f32_e32 v181, v121
	v_pk_add_f32 v[112:113], v[162:163], v[112:113]
	v_exp_f32_e32 v179, v122
	v_pk_add_f32 v[112:113], v[168:169], v[112:113]
	v_exp_f32_e32 v183, v123
	v_pk_add_f32 v[112:113], v[166:167], v[112:113]
	v_exp_f32_e32 v185, v124
	v_pk_add_f32 v[112:113], v[172:173], v[112:113]
	v_exp_f32_e32 v189, v125
	v_pk_add_f32 v[112:113], v[170:171], v[112:113]
	v_exp_f32_e32 v187, v126
	v_pk_add_f32 v[112:113], v[176:177], v[112:113]
	v_exp_f32_e32 v119, v127
	v_pk_add_f32 v[112:113], v[174:175], v[112:113]
	v_pk_add_f32 v[114:115], v[204:205], v[204:205] op_sel:[0,1] op_sel_hi:[1,0]
	v_pk_add_f32 v[112:113], v[180:181], v[112:113]
	v_mov_b32_e32 v115, v119
	v_pk_add_f32 v[112:113], v[178:179], v[112:113]
	v_cvt_pk_bf16_f32 v116, v175, v181
	v_pk_add_f32 v[112:113], v[182:183], v[112:113]
	v_cvt_pk_bf16_f32 v117, v179, v183
	v_pk_add_f32 v[112:113], v[184:185], v[112:113]
	v_cvt_pk_bf16_f32 v118, v185, v189
	v_pk_add_f32 v[112:113], v[188:189], v[112:113]
	v_cvt_pk_bf16_f32 v119, v187, v119
	v_pk_add_f32 v[112:113], v[186:187], v[112:113]
	s_nop 0
	v_pk_add_f32 v[112:113], v[114:115], v[112:113]
	v_cvt_pk_bf16_f32 v114, v167, v173
	v_add_f32_e32 v176, v112, v113
	v_cvt_pk_bf16_f32 v112, v161, v165
	v_cvt_pk_bf16_f32 v113, v163, v169
	v_cvt_pk_bf16_f32 v115, v171, v177
	s_waitcnt lgkmcnt(7)
	s_nop 0
	v_mfma_f32_32x32x16_bf16 v[48:63], v[156:159], v[112:115], v[48:63]
	s_waitcnt lgkmcnt(6)
	v_mfma_f32_32x32x16_bf16 v[32:47], v[152:155], v[112:115], v[32:47]
	s_waitcnt lgkmcnt(3)
	v_mfma_f32_32x32x16_bf16 v[16:31], v[148:151], v[112:115], v[16:31]
	s_waitcnt lgkmcnt(2)
	v_mfma_f32_32x32x16_bf16 v[0:15], v[144:147], v[112:115], v[0:15]
	v_mfma_f32_32x32x16_bf16 v[48:63], v[108:111], v[116:119], v[48:63]
	v_mfma_f32_32x32x16_bf16 v[32:47], v[104:107], v[116:119], v[32:47]
	s_waitcnt lgkmcnt(1)
	v_mfma_f32_32x32x16_bf16 v[16:31], v[96:99], v[116:119], v[16:31]
	v_mov_b32_e32 v96, v190
	s_nop 1
	v_permlane32_swap_b32_e32 v190, v96
	v_max_f32_e32 v96, v96, v96
	v_max_f32_e32 v97, v190, v190
	v_max_f32_e32 v96, v97, v96
	v_cmp_lt_f32_e32 vcc, s95, v96
	s_waitcnt lgkmcnt(0)
	v_mfma_f32_32x32x16_bf16 v[0:15], v[100:103], v[116:119], v[0:15]
	s_cbranch_vccz .LBB0_289
; DI float swap_max(float m) { auto rr = __builtin_amdgcn_permlane32_swap(__float_as_uint(m), __float_as_uint(m), false, false); return fmaxf(__uint_as_float(rr[0]), __uint_as_float(rr[1])); }
; DI float ex2(float x) { return __builtin_amdgcn_exp2f(x); }
; DI void attn_renorm(f32x16& spend, f32x16 (&O)[4], f32x16& negm, float& mref, float& lsum, float& mrun) {
;     constexpr float THR = 6.0f;
;     const float mx = swap_max(mrun);
;     if (__any(mx > THR)) {
;         const float dl = fmaxf(mx, 0.f), alpha = ex2(-dl);
;         mref += dl; lsum *= alpha;
; #pragma unroll
;         for (int cb = 0; cb < 4; ++cb) O[cb] = O[cb] * alpha;
; #pragma unroll
;         for (int i = 0; i < 16; ++i) { spend[i] -= dl; negm[i] = -mref; }
;     }
;     mrun = -1.0e30f;
; }
	v_max_f32_e32 v64, v96, v96
	v_max_f32_e32 v65, 0, v64
	v_exp_f32_e64 v64, -v65
	v_add_f32_e32 v200, v200, v65
	v_sub_f32_e32 v95, v95, v65
	v_sub_f32_e32 v94, v94, v65
	v_mul_f32_e32 v176, v176, v64
	v_pk_mul_f32 v[62:63], v[62:63], v[64:65] op_sel_hi:[1,0]
	v_pk_mul_f32 v[60:61], v[60:61], v[64:65] op_sel_hi:[1,0]
	v_pk_mul_f32 v[58:59], v[58:59], v[64:65] op_sel_hi:[1,0]
	v_pk_mul_f32 v[56:57], v[56:57], v[64:65] op_sel_hi:[1,0]
	v_pk_mul_f32 v[54:55], v[54:55], v[64:65] op_sel_hi:[1,0]
	v_pk_mul_f32 v[52:53], v[52:53], v[64:65] op_sel_hi:[1,0]
	v_pk_mul_f32 v[50:51], v[50:51], v[64:65] op_sel_hi:[1,0]
	v_pk_mul_f32 v[48:49], v[48:49], v[64:65] op_sel_hi:[1,0]
	v_pk_mul_f32 v[46:47], v[46:47], v[64:65] op_sel_hi:[1,0]
	v_pk_mul_f32 v[44:45], v[44:45], v[64:65] op_sel_hi:[1,0]
	v_pk_mul_f32 v[42:43], v[42:43], v[64:65] op_sel_hi:[1,0]
	v_pk_mul_f32 v[40:41], v[40:41], v[64:65] op_sel_hi:[1,0]
	v_pk_mul_f32 v[38:39], v[38:39], v[64:65] op_sel_hi:[1,0]
	v_pk_mul_f32 v[36:37], v[36:37], v[64:65] op_sel_hi:[1,0]
	v_pk_mul_f32 v[34:35], v[34:35], v[64:65] op_sel_hi:[1,0]
	v_pk_mul_f32 v[32:33], v[32:33], v[64:65] op_sel_hi:[1,0]
	v_pk_mul_f32 v[30:31], v[30:31], v[64:65] op_sel_hi:[1,0]
	v_pk_mul_f32 v[28:29], v[28:29], v[64:65] op_sel_hi:[1,0]
	v_pk_mul_f32 v[26:27], v[26:27], v[64:65] op_sel_hi:[1,0]
	v_pk_mul_f32 v[24:25], v[24:25], v[64:65] op_sel_hi:[1,0]
	v_pk_mul_f32 v[22:23], v[22:23], v[64:65] op_sel_hi:[1,0]
	v_pk_mul_f32 v[20:21], v[20:21], v[64:65] op_sel_hi:[1,0]
	v_pk_mul_f32 v[18:19], v[18:19], v[64:65] op_sel_hi:[1,0]
	v_pk_mul_f32 v[16:17], v[16:17], v[64:65] op_sel_hi:[1,0]
	v_pk_mul_f32 v[14:15], v[14:15], v[64:65] op_sel_hi:[1,0]
	v_pk_mul_f32 v[12:13], v[12:13], v[64:65] op_sel_hi:[1,0]
	v_pk_mul_f32 v[10:11], v[10:11], v[64:65] op_sel_hi:[1,0]
	v_pk_mul_f32 v[8:9], v[8:9], v[64:65] op_sel_hi:[1,0]
	v_pk_mul_f32 v[6:7], v[6:7], v[64:65] op_sel_hi:[1,0]
	v_pk_mul_f32 v[4:5], v[4:5], v[64:65] op_sel_hi:[1,0]
	v_pk_mul_f32 v[2:3], v[2:3], v[64:65] op_sel_hi:[1,0]
	v_pk_mul_f32 v[0:1], v[0:1], v[64:65] op_sel_hi:[1,0]
	v_xor_b32_e32 v64, 0x80000000, v200
	v_sub_f32_e32 v93, v93, v65
	v_sub_f32_e32 v92, v92, v65
	v_sub_f32_e32 v91, v91, v65
	v_sub_f32_e32 v90, v90, v65
	v_sub_f32_e32 v89, v89, v65
	v_sub_f32_e32 v88, v88, v65
	v_sub_f32_e32 v87, v87, v65
	v_sub_f32_e32 v86, v86, v65
	v_sub_f32_e32 v85, v85, v65
	v_sub_f32_e32 v84, v84, v65
	v_sub_f32_e32 v83, v83, v65
	v_sub_f32_e32 v82, v82, v65
	v_sub_f32_e32 v81, v81, v65
	v_sub_f32_e32 v80, v80, v65
	v_mov_b32_e32 v65, v64
	v_mov_b32_e32 v66, v64
	v_mov_b32_e32 v67, v64
	v_mov_b32_e32 v68, v64
	v_mov_b32_e32 v69, v64
	v_mov_b32_e32 v70, v64
	v_mov_b32_e32 v71, v64
	v_mov_b32_e32 v72, v64
	v_mov_b32_e32 v73, v64
	v_mov_b32_e32 v74, v64
	v_mov_b32_e32 v75, v64
	v_mov_b32_e32 v76, v64
	v_mov_b32_e32 v77, v64
	v_mov_b32_e32 v78, v64
	v_mov_b32_e32 v79, v64
	s_branch .LBB0_289
.Lrenorm_a:
	v_max_f32_e32 v64, v80, v80
	v_max_f32_e32 v65, 0, v64
	v_exp_f32_e64 v64, -v65
	v_add_f32_e32 v200, v200, v65
	v_xor_b32_e32 v80, 0x80000000, v200
	v_sub_f32_e32 v111, v111, v65
	v_mul_f32_e32 v202, v202, v64
	v_pk_mul_f32 v[62:63], v[62:63], v[64:65] op_sel_hi:[1,0]
	v_pk_mul_f32 v[60:61], v[60:61], v[64:65] op_sel_hi:[1,0]
	v_pk_mul_f32 v[58:59], v[58:59], v[64:65] op_sel_hi:[1,0]
	v_pk_mul_f32 v[56:57], v[56:57], v[64:65] op_sel_hi:[1,0]
	v_pk_mul_f32 v[54:55], v[54:55], v[64:65] op_sel_hi:[1,0]
	v_pk_mul_f32 v[52:53], v[52:53], v[64:65] op_sel_hi:[1,0]
	v_pk_mul_f32 v[50:51], v[50:51], v[64:65] op_sel_hi:[1,0]
	v_pk_mul_f32 v[48:49], v[48:49], v[64:65] op_sel_hi:[1,0]
	v_pk_mul_f32 v[46:47], v[46:47], v[64:65] op_sel_hi:[1,0]
	v_pk_mul_f32 v[44:45], v[44:45], v[64:65] op_sel_hi:[1,0]
	v_pk_mul_f32 v[42:43], v[42:43], v[64:65] op_sel_hi:[1,0]
	v_pk_mul_f32 v[40:41], v[40:41], v[64:65] op_sel_hi:[1,0]
	v_pk_mul_f32 v[38:39], v[38:39], v[64:65] op_sel_hi:[1,0]
	v_pk_mul_f32 v[36:37], v[36:37], v[64:65] op_sel_hi:[1,0]
	v_pk_mul_f32 v[34:35], v[34:35], v[64:65] op_sel_hi:[1,0]
	v_pk_mul_f32 v[32:33], v[32:33], v[64:65] op_sel_hi:[1,0]
	v_pk_mul_f32 v[30:31], v[30:31], v[64:65] op_sel_hi:[1,0]
	v_pk_mul_f32 v[28:29], v[28:29], v[64:65] op_sel_hi:[1,0]
	v_pk_mul_f32 v[26:27], v[26:27], v[64:65] op_sel_hi:[1,0]
	v_pk_mul_f32 v[24:25], v[24:25], v[64:65] op_sel_hi:[1,0]
	v_pk_mul_f32 v[22:23], v[22:23], v[64:65] op_sel_hi:[1,0]
	v_pk_mul_f32 v[20:21], v[20:21], v[64:65] op_sel_hi:[1,0]
	v_pk_mul_f32 v[18:19], v[18:19], v[64:65] op_sel_hi:[1,0]
	v_pk_mul_f32 v[16:17], v[16:17], v[64:65] op_sel_hi:[1,0]
	v_pk_mul_f32 v[14:15], v[14:15], v[64:65] op_sel_hi:[1,0]
	v_pk_mul_f32 v[12:13], v[12:13], v[64:65] op_sel_hi:[1,0]
	v_pk_mul_f32 v[10:11], v[10:11], v[64:65] op_sel_hi:[1,0]
	v_pk_mul_f32 v[8:9], v[8:9], v[64:65] op_sel_hi:[1,0]
	v_pk_mul_f32 v[6:7], v[6:7], v[64:65] op_sel_hi:[1,0]
	v_pk_mul_f32 v[4:5], v[4:5], v[64:65] op_sel_hi:[1,0]
	v_pk_mul_f32 v[2:3], v[2:3], v[64:65] op_sel_hi:[1,0]
	v_pk_mul_f32 v[0:1], v[0:1], v[64:65] op_sel_hi:[1,0]
	v_sub_f32_e32 v110, v110, v65
	v_sub_f32_e32 v109, v109, v65
	v_sub_f32_e32 v108, v108, v65
	v_sub_f32_e32 v107, v107, v65
	v_sub_f32_e32 v106, v106, v65
	v_sub_f32_e32 v105, v105, v65
	v_sub_f32_e32 v104, v104, v65
	v_sub_f32_e32 v103, v103, v65
	v_sub_f32_e32 v102, v102, v65
	v_sub_f32_e32 v101, v101, v65
	v_sub_f32_e32 v100, v100, v65
	v_sub_f32_e32 v99, v99, v65
	v_sub_f32_e32 v98, v98, v65
	v_sub_f32_e32 v97, v97, v65
	v_sub_f32_e32 v96, v96, v65
	v_mov_b32_e32 v81, v80
	v_mov_b32_e32 v82, v80
	v_mov_b32_e32 v83, v80
	v_mov_b32_e32 v84, v80
	v_mov_b32_e32 v85, v80
	v_mov_b32_e32 v86, v80
	v_mov_b32_e32 v87, v80
	v_mov_b32_e32 v88, v80
	v_mov_b32_e32 v89, v80
	v_mov_b32_e32 v90, v80
	v_mov_b32_e32 v91, v80
	v_mov_b32_e32 v92, v80
	v_mov_b32_e32 v93, v80
	v_mov_b32_e32 v94, v80
	v_mov_b32_e32 v95, v80
	v_mov_b32_e32 v64, v80
	v_mov_b32_e32 v65, v80
	v_mov_b32_e32 v66, v80
	v_mov_b32_e32 v67, v80
	v_mov_b32_e32 v68, v80
	v_mov_b32_e32 v69, v80
	v_mov_b32_e32 v70, v80
	v_mov_b32_e32 v71, v80
	v_mov_b32_e32 v72, v80
	v_mov_b32_e32 v73, v80
	v_mov_b32_e32 v74, v80
	v_mov_b32_e32 v75, v80
	v_mov_b32_e32 v76, v80
	v_mov_b32_e32 v77, v80
	v_mov_b32_e32 v78, v80
	v_mov_b32_e32 v79, v80
	s_branch .LBB0_293
